# masked attention loop: two key tiles per workgroup barrier (LDS ring of 4)
# speedup vs baseline: 1.0139x; 1.0011x over previous
; #define ATT_LAS __attribute__((address_space(3)))
; __device__ __forceinline__ int crow(int r, int hi) { return (r & 3) + 8 * (r >> 2) + 4 * hi; }
; __device__ __forceinline__ void attn_unit(int uv, const float* sink_l, const bf16_t* P, bf16_t* Y, ATT_LAS unsigned char* lds, const float* rpb_l, const float* qn_l, const float* kn_l) {
;     ...
;     if (a.mode != 0 && nlat > 0) {
;         u32x4 kreg, vreg;
;         { const size_t ro = (size_t)ATT_TROW(4) * PITCH; kreg = *(const u32x4*)(kg + ro); vreg = *(const u32x4*)(vg + ro); }
;         *(ATT_LAS u32x4*)(ATT_KBUF(0) + koff) = kreg; *(ATT_LAS u32x4*)(ATT_VBUF(0) + voff) = vreg;
;         __syncthreads();
;         const int qw = a.qpos0 + 32 * wid, qr = qw >> 6;
;     ...
;                 else { const int qc = 32 * (wid & 1) + r32, cs = clampi(qc - 8, 0, 48); const ATT_LAS float* trow = tbl + (tl - qr + 7) * 31 + 15 - qc;
; #pragma unroll
;                     for (int r = 0; r < 16; ++r) { const int kcl = crow(r, hi);
.Lmk_pre:
	s_lshl_b32 s92, s93, 6
	s_add_i32 s84, s27, s92
	v_lshrrev_b32_e32 v116, 6, v192
	v_and_b32_e32 v117, 63, v192
	v_lshrrev_b32_e32 v118, 3, v117
	v_sub_u32_e32 v118, v118, v116
	v_mul_i32_i24_e32 v244, 0x8ff0, v118
	v_ashrrev_i32_e32 v245, 31, v244
	v_and_b32_e32 v118, 3, v116
	v_lshlrev_b32_e32 v118, 4, v118
	v_lshlrev_b32_e32 v119, 3, v116
	v_sub_u32_e32 v118, v118, v119
	v_bfe_u32 v119, v117, 3, 1
	v_bfe_u32 v204, v117, 4, 1
	v_bfe_u32 v205, v117, 5, 1
	v_add_u32_e32 v208, v119, v204
	v_lshl_add_u32 v208, v205, 1, v208
	v_lshl_add_u32 v118, v208, 1, v118
	v_lshrrev_b32_e32 v209, 2, v116
	v_sub_u32_e32 v209, v209, v119
	v_mul_i32_i24_e32 v118, 0x1200, v118
	v_lshl_add_u32 v246, v209, 6, v118
	v_ashrrev_i32_e32 v247, 31, v246
	v_readfirstlane_b32 s100, v116
	s_mov_b64 s[98:99], 0x48000
	s_lshl_b32 s100, s100, 10
	v_mad_i64_i32 v[116:117], s[0:1], s84, v215, v[198:199]
	v_mad_i64_i32 v[118:119], s[0:1], s84, v215, v[200:201]
	v_lshl_add_u64 v[116:117], v[244:245], 0, v[116:117]
	v_lshl_add_u64 v[118:119], v[246:247], 0, v[118:119]
	v_mad_i64_i32 v[112:113], s[0:1], s30, v215, v[198:199]
	v_mad_i64_i32 v[114:115], s[0:1], s30, v215, v[200:201]
	v_lshl_add_u64 v[112:113], v[244:245], 0, v[112:113]
	v_lshl_add_u64 v[114:115], v[246:247], 0, v[114:115]
	s_mov_b32 m0, s100
	s_nop 0
	global_load_lds_dwordx4 v[112:113], off
	s_add_i32 s101, s100, 0x6000
	s_mov_b32 m0, s101
	s_nop 0
	global_load_lds_dwordx4 v[114:115], off
	v_lshl_add_u64 v[112:113], v[112:113], 0, s[98:99]
	v_lshl_add_u64 v[114:115], v[114:115], 0, s[98:99]
	s_add_i32 s101, s100, 0x2000
	s_mov_b32 m0, s101
	s_nop 0
	global_load_lds_dwordx4 v[112:113], off
	s_add_i32 s101, s100, 0x8000
	s_mov_b32 m0, s101
	s_nop 0
	global_load_lds_dwordx4 v[114:115], off
	v_lshl_add_u64 v[112:113], v[112:113], 0, s[98:99]
	v_lshl_add_u64 v[114:115], v[114:115], 0, s[98:99]
	v_and_or_b32 v32, s28, 32, v223
	v_subrev_co_u32_e32 v32, vcc, 8, v32
	v_min_u32_e32 v32, 48, v32
	v_or_b32_e32 v33, 32, v219
	v_cndmask_b32_e64 v32, v32, 0, vcc
	v_or_b32_e32 v50, 17, v219
	v_sub_u32_e32 v33, v33, v32
	v_or_b32_e32 v51, 49, v219
	v_cmp_gt_u32_e64 s[68:69], 16, v33
	v_sub_u32_e32 v33, v50, v32
	v_or_b32_e32 v34, 1, v219
	v_cmp_gt_u32_e64 s[40:41], 16, v33
	v_sub_u32_e32 v33, v51, v32
	v_sub_u32_e32 v34, v34, v32
	v_cmp_gt_u32_e64 s[42:43], 16, v33
	v_or_b32_e32 v33, 18, v219
	v_cmp_gt_u32_e64 s[4:5], 16, v34
	v_or_b32_e32 v34, 50, v219
	v_sub_u32_e32 v33, v33, v32
	v_cmp_gt_u32_e64 s[44:45], 16, v33
	v_sub_u32_e32 v33, v34, v32
	v_cmp_gt_u32_e64 s[46:47], 16, v33
	v_or_b32_e32 v33, 19, v219
	v_or_b32_e32 v34, 51, v219
	v_sub_u32_e32 v33, v33, v32
	v_cmp_gt_u32_e64 s[48:49], 16, v33
	v_sub_u32_e32 v33, v34, v32
	v_cmp_gt_u32_e64 s[50:51], 16, v33
	v_or_b32_e32 v33, 24, v219
	v_or_b32_e32 v34, 56, v219
	v_sub_u32_e32 v33, v33, v32
	v_cmp_gt_u32_e64 s[52:53], 16, v33
	v_sub_u32_e32 v33, v34, v32
	s_add_i32 s85, s28, s26
	v_cmp_gt_u32_e64 s[54:55], 16, v33
	v_or_b32_e32 v33, 25, v219
	s_ashr_i32 s82, s85, 6
	v_or_b32_e32 v34, 57, v219
	v_sub_u32_e32 v33, v33, v32
	s_add_i32 s0, s82, -4
	v_cmp_gt_u32_e64 s[56:57], 16, v33
	v_sub_u32_e32 v33, v34, v32
	s_min_u32 s0, s0, 0x78
	v_cmp_gt_u32_e64 s[58:59], 16, v33
	v_or_b32_e32 v33, 26, v219
	s_cmp_gt_i32 s82, 3
	v_or_b32_e32 v34, 58, v219
	v_sub_u32_e32 v33, v33, v32
	s_cselect_b32 s79, s0, 0
	v_cmp_gt_u32_e64 s[60:61], 16, v33
	v_sub_u32_e32 v33, v34, v32
	v_or_b32_e32 v35, 33, v219
	v_or_b32_e32 v36, 2, v219
	v_or_b32_e32 v37, 34, v219
	v_or_b32_e32 v38, 3, v219
	v_or_b32_e32 v39, 35, v219
	v_or_b32_e32 v40, 8, v219
	v_or_b32_e32 v41, 40, v219
	v_or_b32_e32 v42, 9, v219
	v_or_b32_e32 v43, 41, v219
	v_or_b32_e32 v44, 10, v219
	v_or_b32_e32 v45, 42, v219
	v_or_b32_e32 v46, 11, v219
	v_or_b32_e32 v47, 43, v219
	v_or_b32_e32 v48, 16, v219
	v_or_b32_e32 v49, 48, v219
	s_add_i32 s33, s85, 0xffffff80
	s_add_i32 s91, s85, 0x9f
	s_add_i32 s6, s79, 8
	v_cmp_gt_u32_e64 s[62:63], 16, v33
	v_or_b32_e32 v33, 27, v219
	v_or_b32_e32 v34, 59, v219
	s_lshl_b64 s[66:67], s[72:73], 1
	v_readlane_b32 vcc_lo, v255, 29
	v_sub_u32_e32 v52, v219, v32
	v_sub_u32_e32 v35, v35, v32
	v_sub_u32_e32 v36, v36, v32
	v_sub_u32_e32 v37, v37, v32
	v_sub_u32_e32 v38, v38, v32
	v_sub_u32_e32 v39, v39, v32
	v_sub_u32_e32 v40, v40, v32
	v_sub_u32_e32 v41, v41, v32
	v_sub_u32_e32 v42, v42, v32
	v_sub_u32_e32 v43, v43, v32
	v_sub_u32_e32 v44, v44, v32
	v_sub_u32_e32 v45, v45, v32
	v_sub_u32_e32 v46, v46, v32
	v_sub_u32_e32 v47, v47, v32
	v_sub_u32_e32 v48, v48, v32
	v_sub_u32_e32 v49, v49, v32
	v_sub_u32_e32 v33, v33, v32
	v_sub_u32_e32 v32, v34, v32
	v_readlane_b32 vcc_hi, v255, 30
	s_add_u32 s86, vcc_lo, s66
	s_movk_i32 s83, 0x1200
	s_addc_u32 s87, vcc_hi, s67
	v_cmp_gt_u32_e64 s[66:67], 16, v32
	v_add_u32_e32 v32, s37, v227
	v_cmp_gt_u32_e64 s[64:65], 16, v33
	v_mad_i64_i32 v[32:33], s[96:97], v32, s83, 0
	v_mad_i64_i32 v[32:33], s[96:97], s84, v215, v[32:33]
	s_movk_i32 s72, 0x70
	v_and_or_b32 v32, v230, s72, v32
	s_mul_hi_i32 s72, s84, 0x1200
	s_mulk_i32 s84, 0x1200
	s_lshl_b64 s[80:81], s[80:81], 1
	s_add_u32 s80, s80, s84
	s_addc_u32 s81, s81, s72
	v_lshl_add_u64 v[120:121], s[86:87], 0, v[32:33]
	v_add3_u32 v34, s37, v226, v225
	v_mov_b64_e32 v[32:33], s[80:81]
	v_mad_i64_i32 v[32:33], s[80:81], v34, s83, v[32:33]
	v_add_lshl_u32 v196, v228, v229, 1
	v_lshl_add_u64 v[32:33], v[32:33], 0, v[196:197]
	v_lshl_add_u64 v[122:123], vcc, 0, v[32:33]
	v_add_u32_e32 v32, s85, v223
	s_mul_i32 s72, s93, 0x7c
	v_sub_u32_e32 v126, v219, v32
	v_lshl_add_u32 v32, v224, 4, s72
	v_lshlrev_b32_e32 v33, 2, v223
	v_sub_u32_e32 v32, v32, v33
	s_mulk_i32 s82, 0x7c
	v_subrev_u32_e32 v32, s82, v32
	s_and_b32 s72, s34, 0x80
	v_subrev_u32_e32 v32, s72, v32
	v_readlane_b32 s72, v255, 31
	v_add_u32_e32 v125, s35, v231
	s_mov_b32 s7, 0
	v_cmp_gt_u32_e64 s[0:1], 16, v52
	v_cmp_gt_u32_e64 s[8:9], 16, v35
	v_cmp_gt_u32_e64 s[10:11], 16, v36
	v_cmp_gt_u32_e64 s[12:13], 16, v37
	v_cmp_gt_u32_e64 s[14:15], 16, v38
	v_cmp_gt_u32_e64 s[16:17], 16, v39
	v_cmp_gt_u32_e64 s[18:19], 16, v40
	v_cmp_gt_u32_e64 s[20:21], 16, v41
	v_cmp_gt_u32_e64 s[22:23], 16, v42
	v_cmp_gt_u32_e64 s[24:25], 16, v43
	v_cmp_gt_u32_e64 s[26:27], 16, v44
	v_cmp_gt_u32_e64 s[28:29], 16, v45
	v_cmp_gt_u32_e64 s[30:31], 16, v46
	v_cmp_gt_u32_e64 s[94:95], 16, v47
	v_cmp_gt_u32_e64 s[76:77], 16, v48
	v_cmp_gt_u32_e64 s[38:39], 16, v49
	v_add_u32_e32 v127, s72, v32
	s_mov_b32 s32, 0
	s_sub_i32 s93, s93, 4
	s_sub_i32 s92, s92, 0x100
	v_subrev_u32_e32 v127, 0x1f0, v127
	s_add_i32 s71, s71, 4
	s_waitcnt vmcnt(0)
	s_waitcnt lgkmcnt(0)
	s_barrier
; __device__ __forceinline__ void attn_unit(int uv, const float* sink_l, const bf16_t* P, bf16_t* Y, ATT_LAS unsigned char* lds, const float* rpb_l, const float* qn_l, const float* kn_l) {
;     ...
;         for (int t = 0; t < nlat; ++t) {
;             const int cur = t & 1, tl = a.t_lo + t;
;             if (t + 1 < nlat) { const size_t ro = (size_t)ATT_TROW(t + 5) * PITCH; kreg = *(const u32x4*)(kg + ro); vreg = *(const u32x4*)(vg + ro); }
;             bool need;
;             if (a.mode == 1) need = (tl * 64 + 63 >= qw - 128) && (tl * 64 <= qw + 31 + 128);
;             else { const int rs = clampi(qr - 4, 0, 120); need = (tl >= rs) && (tl < rs + 8); }
.Lmk_top:
	s_add_i32 s96, s7, 2
	s_cmp_lt_i32 s96, s71
	s_cbranch_scc0 .Lmk_nodma2
	s_cmp_eq_u32 s96, 4
	s_cbranch_scc0 .Lmk_noswitch
	v_mov_b32_e32 v112, v116
	v_mov_b32_e32 v113, v117
	v_mov_b32_e32 v114, v118
	v_mov_b32_e32 v115, v119
.Lmk_noswitch:
	s_add_i32 s80, s32, 2
	s_and_b32 s80, s80, 3
	s_lshl_b32 s81, s80, 13
	s_cmp_eq_u32 s80, 3
	s_cselect_b32 s81, 0xe000, s81
	s_lshl_b32 s96, s80, 13
	s_cmp_eq_u32 s80, 2
	s_cselect_b32 s96, 0x6000, s96
	s_cmp_eq_u32 s80, 3
	s_cselect_b32 s96, 0xa000, s96
	s_add_i32 s96, s96, 0x6000
	s_add_i32 s81, s81, s100
	s_mov_b32 m0, s81
	s_nop 0
	global_load_lds_dwordx4 v[112:113], off
	s_add_i32 s96, s96, s100
	s_mov_b32 m0, s96
	s_nop 0
	global_load_lds_dwordx4 v[114:115], off
	v_lshl_add_u64 v[112:113], v[112:113], 0, s[98:99]
	v_lshl_add_u64 v[114:115], v[114:115], 0, s[98:99]
.Lmk_nodma2:
	s_add_i32 s96, s7, 3
	s_cmp_lt_i32 s96, s71
	s_cbranch_scc0 .Lmk_nodma3
	s_add_i32 s80, s32, 3
	s_and_b32 s80, s80, 3
	s_lshl_b32 s81, s80, 13
	s_cmp_eq_u32 s80, 3
	s_cselect_b32 s81, 0xe000, s81
	s_lshl_b32 s96, s80, 13
	s_cmp_eq_u32 s80, 2
	s_cselect_b32 s96, 0x6000, s96
	s_cmp_eq_u32 s80, 3
	s_cselect_b32 s96, 0xa000, s96
	s_add_i32 s96, s96, 0x6000
	s_add_i32 s81, s81, s100
	s_mov_b32 m0, s81
	s_nop 0
	global_load_lds_dwordx4 v[112:113], off
	s_add_i32 s96, s96, s100
	s_mov_b32 m0, s96
	s_nop 0
	global_load_lds_dwordx4 v[114:115], off
	v_lshl_add_u64 v[112:113], v[112:113], 0, s[98:99]
	v_lshl_add_u64 v[114:115], v[114:115], 0, s[98:99]
.Lmk_nodma3:
.Lmk_tile:
	s_cmp_lt_i32 s7, 4
	s_cbranch_scc1 .LBB0_657
	s_and_b64 vcc, exec, s[2:3]
	s_cbranch_vccz .Lmk_need_win
	s_add_i32 s72, s93, s7
	s_cmp_ge_i32 s72, s79
	s_cbranch_scc0 .Lmsk_tail
	s_cmp_lt_i32 s72, s6
	s_cbranch_scc0 .Lmsk_tail
	s_branch .LBB0_657

; #define ATT_LAS __attribute__((address_space(3)))
; __device__ __forceinline__ void attn_unit(int uv, const float* sink_l, const bf16_t* P, bf16_t* Y, ATT_LAS unsigned char* lds, const float* rpb_l, const float* qn_l, const float* kn_l) {
;     ...
;                 const ATT_LAS unsigned char* Kb = ATT_KBUF(cur); const ATT_LAS unsigned char* Vb = ATT_VBUF(cur);
;                 f32x16 p0 = {}, p1 = {};
; #pragma unroll
;                 for (int d0 = 0; d0 < 4; ++d0) {
;                     const bf16x8 k0 = *(const ATT_LAS bf16x8*)(Kb + kfrag + d0 * 2048);
;                     const bf16x8 k1 = *(const ATT_LAS bf16x8*)(Kb + kfrag + d0 * 2048 + 512);
.LBB0_657:
	s_lshl_b32 s86, s32, 13
	s_cmp_eq_u32 s32, 3
	s_cselect_b32 s86, 0xe000, s86
	s_lshl_b32 s87, s32, 13
	s_cmp_eq_u32 s32, 2
	s_cselect_b32 s87, 0x6000, s87
	s_cmp_eq_u32 s32, 3
	s_cselect_b32 s87, 0xa000, s87
	v_add_u32_e32 v40, s86, v221
	v_add_u32_e32 v242, s87, v125
	ds_read_b128 v[128:131], v40
	ds_read_b128 v[132:135], v40 offset:512
	ds_read_b128 v[136:139], v40 offset:2048
	ds_read_b128 v[140:143], v40 offset:2560
	ds_read_b128 v[144:147], v40 offset:4096
	ds_read_b128 v[148:151], v40 offset:4608
	ds_read_b128 v[152:155], v40 offset:6144
	ds_read_b128 v[156:159], v40 offset:6656
	s_cmp_lt_i32 s7, 4
	s_cbranch_scc0 .Lmk_lat

; #define ATT_LAS __attribute__((address_space(3)))
; __device__ __forceinline__ void attn_unit(int uv, const float* sink_l, const bf16_t* P, bf16_t* Y, ATT_LAS unsigned char* lds, const float* rpb_l, const float* qn_l, const float* kn_l) {
;     ...
;         for (int t = 0; t < nlat; ++t) {
;     ...
;             if (t + 1 < nlat) { *(ATT_LAS u32x4*)(ATT_KBUF(cur ^ 1) + koff) = kreg; *(ATT_LAS u32x4*)(ATT_VBUF(cur ^ 1) + voff) = vreg; }
;             __syncthreads();
.Lmsk_tail:
	s_add_i32 s92, s92, 64
	v_add_u32_e32 v127, 0x7c, v127
	s_add_i32 s7, s7, 1
	s_add_i32 s32, s32, 1
	s_and_b32 s32, s32, 3
	s_cmp_ge_i32 s7, s71
	s_cbranch_scc1 .Lmk_macro_end
	s_bitcmp1_b32 s7, 0
	s_cbranch_scc1 .Lmk_tile
.Lmk_macro_end:
	s_waitcnt vmcnt(0)
	s_waitcnt lgkmcnt(0)
	s_barrier
	s_cmp_lt_i32 s7, s71
	s_cbranch_scc1 .Lmk_top
	s_branch .LBB0_535
